# grid barrier: workgroups that are not their XCD's last arriver poll the top-level generation word directly (no relay through the per-XCD word bumped by the XCD leader after its acquire)
# speedup vs baseline: 1.0003x; 1.0003x over previous
; __device__ __forceinline__ unsigned xb_ld(unsigned* p)              { return __hip_atomic_load(p, __ATOMIC_RELAXED, __HIP_MEMORY_SCOPE_AGENT); }
; __device__ __forceinline__ unsigned xb_add(unsigned* p, unsigned v) { return __hip_atomic_fetch_add(p, v, __ATOMIC_RELAXED, __HIP_MEMORY_SCOPE_AGENT); }
; #define XB_SPIN(cond, bar) do { unsigned _sp = 0; while (cond) { __builtin_amdgcn_s_sleep(1); \
;     if ((++_sp & 255u) == 0u) { if (xb_ld(&(bar)[XB_TMO])) break; if (_sp > XB_SPIN_CAP) { atomicAdd(&(bar)[XB_TMO], 1u); break; } } } } while (0)
; __device__ __forceinline__ void xcd_barrier(const XcdBarrier& b, const int tid0) {
;     ...
;         const unsigned old = xb_add(&bar[XB_XSUB(b.x)], 1u);
;         const unsigned gen = old / nloc;
;         if (old + 1u == (gen + 1u) * nloc) {
;     ...
;         } else {
;             XB_SPIN(xb_ld(&bar[XB_XGEN(b.x)]) == gen, bar);
;             __builtin_amdgcn_fence(__ATOMIC_ACQUIRE, "agent");
.LBB0_4100:
	s_lshl_b32 s2, s52, 8
	s_add_u32 s6, s4, s2
	s_addc_u32 s7, s5, 0
	v_mov_b32_e32 v1, 0x1000
	v_mov_b32_e32 v3, 1
	global_atomic_add v3, v1, v3, s[6:7] offset:1024 sc0
	v_cvt_f32_u32_e32 v1, v2
	v_sub_u32_e32 v4, 0, v2
	v_rcp_iflag_f32_e32 v1, v1
	s_nop 0
	v_mul_f32_e32 v1, 0x4f7ffffe, v1
	v_cvt_u32_f32_e32 v1, v1
	v_mul_lo_u32 v4, v4, v1
	v_mul_hi_u32 v4, v1, v4
	v_add_u32_e32 v1, v1, v4
	s_waitcnt vmcnt(0)
	v_mul_hi_u32 v1, v3, v1
	v_mul_lo_u32 v4, v1, v2
	v_sub_u32_e32 v4, v3, v4
	v_add_u32_e32 v5, 1, v1
	v_cmp_ge_u32_e32 vcc, v4, v2
	v_add_u32_e32 v3, 1, v3
	s_nop 0
	v_cndmask_b32_e32 v1, v1, v5, vcc
	v_sub_u32_e32 v5, v4, v2
	v_cndmask_b32_e32 v4, v4, v5, vcc
	v_add_u32_e32 v5, 1, v1
	v_cmp_ge_u32_e32 vcc, v4, v2
	s_nop 1
	v_cndmask_b32_e32 v1, v1, v5, vcc
	v_mul_lo_u32 v4, v2, v1
	v_add_u32_e32 v2, v4, v2
	v_cmp_ne_u32_e32 vcc, v3, v2
	s_and_saveexec_b64 s[2:3], vcc
	s_xor_b64 s[8:9], exec, s[2:3]
	s_cbranch_execz .LBB0_4114
	s_waitcnt lgkmcnt(0)
	v_mov_b32_e32 v0, 0x3100
	global_load_dword v0, v0, s[4:5] offset:1024 sc1
	s_add_u32 s12, s4, 0x3500
	s_addc_u32 s13, s5, 0
	s_waitcnt vmcnt(0)
	v_cmp_eq_u32_e32 vcc, v0, v1
	s_and_saveexec_b64 s[10:11], vcc
	s_cbranch_execz .LBB0_4113
	s_mov_b32 s2, 1
	s_mov_b64 s[14:15], 0
	v_mov_b32_e32 v0, 0
	s_branch .LBB0_4104

; __device__ __forceinline__ unsigned xb_ld(unsigned* p)              { return __hip_atomic_load(p, __ATOMIC_RELAXED, __HIP_MEMORY_SCOPE_AGENT); }
; __device__ __forceinline__ unsigned xb_add(unsigned* p, unsigned v) { return __hip_atomic_fetch_add(p, v, __ATOMIC_RELAXED, __HIP_MEMORY_SCOPE_AGENT); }
; #define XB_SPIN(cond, bar) do { unsigned _sp = 0; while (cond) { __builtin_amdgcn_s_sleep(1); \
;     if ((++_sp & 255u) == 0u) { if (xb_ld(&(bar)[XB_TMO])) break; if (_sp > XB_SPIN_CAP) { atomicAdd(&(bar)[XB_TMO], 1u); break; } } } } while (0)
; __device__ __forceinline__ void xcd_barrier(const XcdBarrier& b, const int tid0) {
;     ...
;         const unsigned old = xb_add(&bar[XB_XSUB(b.x)], 1u);
;         const unsigned gen = old / nloc;
;         if (old + 1u == (gen + 1u) * nloc) {
;     ...
;         } else {
;             XB_SPIN(xb_ld(&bar[XB_XGEN(b.x)]) == gen, bar);
;             __builtin_amdgcn_fence(__ATOMIC_ACQUIRE, "agent");
.LBB0_4397:
	v_readlane_b32 s6, v254, 1
	s_lshl_b32 s6, s6, 2
	s_add_u32 s6, s4, s6
	s_addc_u32 s7, s5, 0
	v_mov_b32_e32 v1, 0x1000
	v_mov_b32_e32 v3, 1
	global_atomic_add v3, v1, v3, s[6:7] offset:1024 sc0
	v_cvt_f32_u32_e32 v1, v2
	v_sub_u32_e32 v4, 0, v2
	v_rcp_iflag_f32_e32 v1, v1
	s_nop 0
	v_mul_f32_e32 v1, 0x4f7ffffe, v1
	v_cvt_u32_f32_e32 v1, v1
	v_mul_lo_u32 v4, v4, v1
	v_mul_hi_u32 v4, v1, v4
	v_add_u32_e32 v1, v1, v4
	s_waitcnt vmcnt(0)
	v_mul_hi_u32 v1, v3, v1
	v_mul_lo_u32 v4, v1, v2
	v_sub_u32_e32 v4, v3, v4
	v_add_u32_e32 v5, 1, v1
	v_cmp_ge_u32_e32 vcc, v4, v2
	v_add_u32_e32 v3, 1, v3
	s_nop 0
	v_cndmask_b32_e32 v1, v1, v5, vcc
	v_sub_u32_e32 v5, v4, v2
	v_cndmask_b32_e32 v4, v4, v5, vcc
	v_add_u32_e32 v5, 1, v1
	v_cmp_ge_u32_e32 vcc, v4, v2
	s_nop 1
	v_cndmask_b32_e32 v1, v1, v5, vcc
	v_mul_lo_u32 v4, v2, v1
	v_add_u32_e32 v2, v4, v2
	v_cmp_ne_u32_e32 vcc, v3, v2
	s_and_saveexec_b64 s[10:11], vcc
	s_xor_b64 s[10:11], exec, s[10:11]
	s_cbranch_execz .LBB0_4411
	s_waitcnt lgkmcnt(0)
	v_mov_b32_e32 v0, 0x3100
	global_load_dword v0, v0, s[4:5] offset:1024 sc1
	s_add_u32 s16, s4, 0x3500
	s_addc_u32 s17, s5, 0
	s_waitcnt vmcnt(0)
	v_cmp_eq_u32_e32 vcc, v0, v1
	s_and_saveexec_b64 s[12:13], vcc
	s_cbranch_execz .LBB0_4410
	s_mov_b32 s14, 1
	s_mov_b64 s[18:19], 0
	s_branch .LBB0_4401

; __device__ __forceinline__ unsigned xb_ld(unsigned* p)              { return __hip_atomic_load(p, __ATOMIC_RELAXED, __HIP_MEMORY_SCOPE_AGENT); }
; __device__ __forceinline__ unsigned xb_add(unsigned* p, unsigned v) { return __hip_atomic_fetch_add(p, v, __ATOMIC_RELAXED, __HIP_MEMORY_SCOPE_AGENT); }
; #define XB_SPIN(cond, bar) do { unsigned _sp = 0; while (cond) { __builtin_amdgcn_s_sleep(1); \
;     if ((++_sp & 255u) == 0u) { if (xb_ld(&(bar)[XB_TMO])) break; if (_sp > XB_SPIN_CAP) { atomicAdd(&(bar)[XB_TMO], 1u); break; } } } } while (0)
; __device__ __forceinline__ void xcd_barrier(const XcdBarrier& b, const int tid0) {
;     ...
;         const unsigned old = xb_add(&bar[XB_XSUB(b.x)], 1u);
;         const unsigned gen = old / nloc;
;         if (old + 1u == (gen + 1u) * nloc) {
;     ...
;         } else {
;             XB_SPIN(xb_ld(&bar[XB_XGEN(b.x)]) == gen, bar);
;             __builtin_amdgcn_fence(__ATOMIC_ACQUIRE, "agent");
.LBB0_4769:
	v_readlane_b32 s6, v254, 1
	s_lshl_b32 s6, s6, 2
	s_add_u32 s6, s4, s6
	s_addc_u32 s7, s5, 0
	v_mov_b32_e32 v1, 0x1000
	v_mov_b32_e32 v3, 1
	global_atomic_add v3, v1, v3, s[6:7] offset:1024 sc0
	v_cvt_f32_u32_e32 v1, v2
	v_sub_u32_e32 v4, 0, v2
	v_rcp_iflag_f32_e32 v1, v1
	s_nop 0
	v_mul_f32_e32 v1, 0x4f7ffffe, v1
	v_cvt_u32_f32_e32 v1, v1
	v_mul_lo_u32 v4, v4, v1
	v_mul_hi_u32 v4, v1, v4
	v_add_u32_e32 v1, v1, v4
	s_waitcnt vmcnt(0)
	v_mul_hi_u32 v1, v3, v1
	v_mul_lo_u32 v4, v1, v2
	v_sub_u32_e32 v4, v3, v4
	v_add_u32_e32 v5, 1, v1
	v_cmp_ge_u32_e32 vcc, v4, v2
	v_add_u32_e32 v3, 1, v3
	s_nop 0
	v_cndmask_b32_e32 v1, v1, v5, vcc
	v_sub_u32_e32 v5, v4, v2
	v_cndmask_b32_e32 v4, v4, v5, vcc
	v_add_u32_e32 v5, 1, v1
	v_cmp_ge_u32_e32 vcc, v4, v2
	s_nop 1
	v_cndmask_b32_e32 v1, v1, v5, vcc
	v_mul_lo_u32 v4, v2, v1
	v_add_u32_e32 v2, v4, v2
	v_cmp_ne_u32_e32 vcc, v3, v2
	s_and_saveexec_b64 s[8:9], vcc
	s_xor_b64 s[8:9], exec, s[8:9]
	s_cbranch_execz .LBB0_4783
	s_waitcnt lgkmcnt(0)
	v_mov_b32_e32 v0, 0x3100
	global_load_dword v0, v0, s[4:5] offset:1024 sc1
	s_add_u32 s12, s4, 0x3500
	s_addc_u32 s13, s5, 0
	s_waitcnt vmcnt(0)
	v_cmp_eq_u32_e32 vcc, v0, v1
	s_and_saveexec_b64 s[10:11], vcc
	s_cbranch_execz .LBB0_4782
	s_mov_b32 s14, 1
	s_mov_b64 s[16:17], 0
	s_branch .LBB0_4773
